# barrier: the CU's L1 invalidate is issued at arrival right behind the arrival atomic (waited with vmcnt(1)), hidden behind the write-back and the polling; no invalidate after the release
# speedup vs baseline: 1.0123x; 1.0123x over previous
.LBB0_854:
	s_mov_b64 s[6:7], exec
	v_mbcnt_lo_u32_b32 v0, s6, 0
	v_mbcnt_hi_u32_b32 v0, s7, v0
	v_cmp_eq_u32_e32 vcc, 0, v0
	s_and_saveexec_b64 s[2:3], vcc
	s_cbranch_execz .LBB0_856
	s_bcnt1_i32_b64 s5, s[6:7]
	v_readlane_b32 s6, v252, 56
	v_mov_b32_e32 v4, s5
	v_readlane_b32 s7, v252, 57
	s_nop 4
	global_atomic_add v4, v1, v4, s[6:7] sc0
	buffer_inv sc1
.LBB0_856:
	s_or_b64 exec, exec, s[2:3]
	v_cvt_f32_u32_e32 v5, v3
	s_waitcnt vmcnt(1)
	v_readfirstlane_b32 s2, v4
	v_sub_u32_e32 v4, 0, v3
	v_rcp_iflag_f32_e32 v5, v5
	v_add_u32_e32 v6, s2, v0
	v_mul_f32_e32 v5, 0x4f7ffffe, v5
	v_cvt_u32_f32_e32 v5, v5
	v_mul_lo_u32 v0, v4, v5
	v_mul_hi_u32 v0, v5, v0
	v_add_u32_e32 v0, v5, v0
	v_mul_hi_u32 v0, v6, v0
	v_mul_lo_u32 v4, v0, v3
	v_sub_u32_e32 v4, v6, v4
	v_add_u32_e32 v5, 1, v0
	v_cmp_ge_u32_e32 vcc, v4, v3
	s_nop 1
	v_cndmask_b32_e32 v0, v0, v5, vcc
	v_sub_u32_e32 v5, v4, v3
	v_cndmask_b32_e32 v4, v4, v5, vcc
	v_add_u32_e32 v5, 1, v0
	v_cmp_ge_u32_e32 vcc, v4, v3
	v_add_u32_e32 v4, 1, v6
	s_nop 0
	v_cndmask_b32_e32 v0, v0, v5, vcc
	v_mul_lo_u32 v5, v3, v0
	v_add_u32_e32 v3, v5, v3
	v_cmp_ne_u32_e32 vcc, v4, v3
	v_sub_u32_e32 v6, v3, v4
	v_cmp_eq_u32_e64 s[6:7], 1, v6
	s_cbranch_vccz .Lxb_leader
	s_and_b64 s[6:7], s[6:7], exec
	s_cbranch_scc0 .Lxb_poll
	buffer_wbl2 sc1
	s_branch .Lxb_poll

.LBB0_869:
	s_or_b64 exec, exec, s[6:7]
	s_waitcnt vmcnt(0)
.LBB0_870:
	s_andn2_saveexec_b64 s[2:3], s[2:3]
	s_getpc_b64 s[98:99]
